# seams: the acquire-side buffer_inv sc1 is issued before the flag wait (group seams, a_ready, grid barrier) so its latency overlaps the polling
# speedup vs baseline: 1.0060x; 1.0022x over previous
.LBB0_137:
	s_or_b64 exec, exec, s[12:13]
	v_cvt_f32_u32_e32 v5, v3
	s_waitcnt vmcnt(0)
	v_readfirstlane_b32 s3, v4
	v_sub_u32_e32 v4, 0, v3
	v_rcp_iflag_f32_e32 v5, v5
	v_add_u32_e32 v6, s3, v2
	v_mul_f32_e32 v5, 0x4f7ffffe, v5
	v_cvt_u32_f32_e32 v5, v5
	v_mul_lo_u32 v2, v4, v5
	v_mul_hi_u32 v2, v5, v2
	v_add_u32_e32 v2, v5, v2
	v_mul_hi_u32 v2, v6, v2
	v_mul_lo_u32 v4, v2, v3
	v_sub_u32_e32 v4, v6, v4
	v_add_u32_e32 v5, 1, v2
	v_cmp_ge_u32_e32 vcc, v4, v3
	s_nop 1
	v_cndmask_b32_e32 v2, v2, v5, vcc
	v_sub_u32_e32 v5, v4, v3
	v_cndmask_b32_e32 v4, v4, v5, vcc
	v_add_u32_e32 v5, 1, v2
	v_cmp_ge_u32_e32 vcc, v4, v3
	v_add_u32_e32 v4, 1, v6
	s_nop 0
	v_cndmask_b32_e32 v2, v2, v5, vcc
	v_mul_lo_u32 v5, v3, v2
	v_add_u32_e32 v3, v5, v3
	v_cmp_ne_u32_e32 vcc, v4, v3
	s_and_saveexec_b64 s[4:5], vcc
	s_xor_b64 s[10:11], exec, s[4:5]
	s_cbranch_execz .LBB0_151
	s_waitcnt lgkmcnt(0)
	buffer_inv sc1
	v_mov_b32_e32 v1, 0x2000
	global_load_dword v1, v1, s[8:9] offset:1024 sc1
	s_add_u32 s16, s8, 0x2400
	s_addc_u32 s17, s9, 0
	s_waitcnt vmcnt(0)
	v_cmp_eq_u32_e32 vcc, v1, v2
	s_and_saveexec_b64 s[12:13], vcc
	s_cbranch_execz .LBB0_150
	s_add_u32 s14, s72, 0x4200
	s_addc_u32 s15, s73, 0
	s_mov_b32 s3, 1
	s_mov_b64 s[18:19], 0
	v_mov_b32_e32 v1, 0
	s_branch .LBB0_141

.LBB0_150:
	s_or_b64 exec, exec, s[12:13]
	s_waitcnt vmcnt(0)
	s_waitcnt vmcnt(0)
.LBB0_151:
	s_andn2_saveexec_b64 s[4:5], s[10:11]
	s_cbranch_execz .LBB0_171
	s_mov_b64 s[10:11], exec
	buffer_wbl2 sc1
	s_waitcnt lgkmcnt(0)
	s_waitcnt vmcnt(0)
	buffer_inv sc1
	v_mbcnt_lo_u32_b32 v2, s10, 0
	v_mbcnt_hi_u32_b32 v2, s11, v2
	v_cmp_eq_u32_e32 vcc, 0, v2
	s_and_saveexec_b64 s[12:13], vcc
	s_cbranch_execz .LBB0_154
	s_bcnt1_i32_b64 s3, s[10:11]
	v_mov_b32_e32 v3, 0x7000
	v_mov_b32_e32 v4, s3
	global_atomic_add v3, v3, v4, s[72:73] offset:1024 sc0

.LBB0_168:
	s_or_b64 exec, exec, s[10:11]
	s_mov_b64 s[10:11], exec
	v_mbcnt_lo_u32_b32 v1, s10, 0
	v_mbcnt_hi_u32_b32 v1, s11, v1
	v_cmp_eq_u32_e32 vcc, 0, v1
	s_waitcnt vmcnt(0)
	s_and_saveexec_b64 s[12:13], vcc
	s_cbranch_execz .LBB0_170
	s_bcnt1_i32_b64 s3, s[10:11]
	v_mov_b32_e32 v1, 0x2000
	v_mov_b32_e32 v2, s3
	global_atomic_add v1, v2, s[8:9] offset:1024

.LBB0_283:
	s_or_b64 exec, exec, s[10:11]
	v_cvt_f32_u32_e32 v5, v3
	s_waitcnt vmcnt(0)
	v_readfirstlane_b32 s3, v4
	v_sub_u32_e32 v4, 0, v3
	v_rcp_iflag_f32_e32 v5, v5
	v_add_u32_e32 v6, s3, v2
	v_mul_f32_e32 v5, 0x4f7ffffe, v5
	v_cvt_u32_f32_e32 v5, v5
	v_mul_lo_u32 v2, v4, v5
	v_mul_hi_u32 v2, v5, v2
	v_add_u32_e32 v2, v5, v2
	v_mul_hi_u32 v2, v6, v2
	v_mul_lo_u32 v4, v2, v3
	v_sub_u32_e32 v4, v6, v4
	v_add_u32_e32 v5, 1, v2
	v_cmp_ge_u32_e32 vcc, v4, v3
	s_nop 1
	v_cndmask_b32_e32 v2, v2, v5, vcc
	v_sub_u32_e32 v5, v4, v3
	v_cndmask_b32_e32 v4, v4, v5, vcc
	v_add_u32_e32 v5, 1, v2
	v_cmp_ge_u32_e32 vcc, v4, v3
	v_add_u32_e32 v4, 1, v6
	s_nop 0
	v_cndmask_b32_e32 v2, v2, v5, vcc
	v_mul_lo_u32 v5, v3, v2
	v_add_u32_e32 v3, v5, v3
	v_cmp_ne_u32_e32 vcc, v4, v3
	s_and_saveexec_b64 s[4:5], vcc
	s_xor_b64 s[8:9], exec, s[4:5]
	s_cbranch_execz .LBB0_297
	s_waitcnt lgkmcnt(0)
	buffer_inv sc1
	v_mov_b32_e32 v1, 0x2000
	global_load_dword v1, v1, s[6:7] offset:1024 sc1
	s_add_u32 s16, s6, 0x2400
	s_addc_u32 s17, s7, 0
	s_waitcnt vmcnt(0)
	v_cmp_eq_u32_e32 vcc, v1, v2
	s_and_saveexec_b64 s[10:11], vcc
	s_cbranch_execz .LBB0_296
	s_add_u32 s12, s72, 0x4200
	s_addc_u32 s13, s73, 0
	s_mov_b32 s3, 1
	s_mov_b64 s[18:19], 0
	v_mov_b32_e32 v1, 0
	s_branch .LBB0_287

.LBB0_296:
	s_or_b64 exec, exec, s[10:11]
	s_waitcnt vmcnt(0)
	s_waitcnt vmcnt(0)
.LBB0_297:
	s_andn2_saveexec_b64 s[4:5], s[8:9]
	s_cbranch_execz .LBB0_317
	s_mov_b64 s[8:9], exec
	buffer_wbl2 sc1
	s_waitcnt lgkmcnt(0)
	s_waitcnt vmcnt(0)
	buffer_inv sc1
	v_mbcnt_lo_u32_b32 v2, s8, 0
	v_mbcnt_hi_u32_b32 v2, s9, v2
	v_cmp_eq_u32_e32 vcc, 0, v2
	s_and_saveexec_b64 s[10:11], vcc
	s_cbranch_execz .LBB0_300
	s_bcnt1_i32_b64 s3, s[8:9]
	v_mov_b32_e32 v3, 0x7000
	v_mov_b32_e32 v4, s3
	global_atomic_add v3, v3, v4, s[72:73] offset:1024 sc0

.LBB0_314:
	s_or_b64 exec, exec, s[8:9]
	s_mov_b64 s[8:9], exec
	v_mbcnt_lo_u32_b32 v1, s8, 0
	v_mbcnt_hi_u32_b32 v1, s9, v1
	v_cmp_eq_u32_e32 vcc, 0, v1
	s_waitcnt vmcnt(0)
	s_and_saveexec_b64 s[10:11], vcc
	s_cbranch_execz .LBB0_316
	s_bcnt1_i32_b64 s3, s[8:9]
	v_mov_b32_e32 v1, 0x2000
	v_mov_b32_e32 v2, s3
	global_atomic_add v1, v2, s[6:7] offset:1024

.LBB0_476:
	s_or_b64 exec, exec, s[14:15]
	v_cvt_f32_u32_e32 v5, v3
	s_waitcnt vmcnt(0)
	v_readfirstlane_b32 s3, v4
	v_sub_u32_e32 v4, 0, v3
	v_rcp_iflag_f32_e32 v5, v5
	v_add_u32_e32 v6, s3, v2
	v_mul_f32_e32 v5, 0x4f7ffffe, v5
	v_cvt_u32_f32_e32 v5, v5
	v_mul_lo_u32 v2, v4, v5
	v_mul_hi_u32 v2, v5, v2
	v_add_u32_e32 v2, v5, v2
	v_mul_hi_u32 v2, v6, v2
	v_mul_lo_u32 v4, v2, v3
	v_sub_u32_e32 v4, v6, v4
	v_add_u32_e32 v5, 1, v2
	v_cmp_ge_u32_e32 vcc, v4, v3
	s_nop 1
	v_cndmask_b32_e32 v2, v2, v5, vcc
	v_sub_u32_e32 v5, v4, v3
	v_cndmask_b32_e32 v4, v4, v5, vcc
	v_add_u32_e32 v5, 1, v2
	v_cmp_ge_u32_e32 vcc, v4, v3
	v_add_u32_e32 v4, 1, v6
	s_nop 0
	v_cndmask_b32_e32 v2, v2, v5, vcc
	v_mul_lo_u32 v5, v3, v2
	v_add_u32_e32 v3, v5, v3
	v_cmp_ne_u32_e32 vcc, v4, v3
	s_and_saveexec_b64 s[4:5], vcc
	s_xor_b64 s[12:13], exec, s[4:5]
	s_cbranch_execz .LBB0_490
	s_waitcnt lgkmcnt(0)
	buffer_inv sc1
	v_mov_b32_e32 v1, 0x2000
	global_load_dword v1, v1, s[8:9] offset:1024 sc1
	s_add_u32 s18, s8, 0x2400
	s_addc_u32 s19, s9, 0
	s_waitcnt vmcnt(0)
	v_cmp_eq_u32_e32 vcc, v1, v2
	s_and_saveexec_b64 s[14:15], vcc
	s_cbranch_execz .LBB0_489
	s_add_u32 s16, s72, 0x4200
	s_addc_u32 s17, s73, 0
	s_mov_b32 s3, 1
	s_mov_b64 s[20:21], 0
	v_mov_b32_e32 v1, 0
	s_branch .LBB0_480

.LBB0_489:
	s_or_b64 exec, exec, s[14:15]
	s_waitcnt vmcnt(0)
	s_waitcnt vmcnt(0)
.LBB0_490:
	s_andn2_saveexec_b64 s[4:5], s[12:13]
	s_cbranch_execz .LBB0_510
	s_mov_b64 s[12:13], exec
	buffer_wbl2 sc1
	s_waitcnt lgkmcnt(0)
	s_waitcnt vmcnt(0)
	buffer_inv sc1
	v_mbcnt_lo_u32_b32 v2, s12, 0
	v_mbcnt_hi_u32_b32 v2, s13, v2
	v_cmp_eq_u32_e32 vcc, 0, v2
	s_and_saveexec_b64 s[14:15], vcc
	s_cbranch_execz .LBB0_493
	s_bcnt1_i32_b64 s3, s[12:13]
	v_mov_b32_e32 v3, 0x7000
	v_mov_b32_e32 v4, s3
	global_atomic_add v3, v3, v4, s[72:73] offset:1024 sc0

.LBB0_507:
	s_or_b64 exec, exec, s[12:13]
	s_mov_b64 s[12:13], exec
	v_mbcnt_lo_u32_b32 v1, s12, 0
	v_mbcnt_hi_u32_b32 v1, s13, v1
	v_cmp_eq_u32_e32 vcc, 0, v1
	s_waitcnt vmcnt(0)
	s_and_saveexec_b64 s[14:15], vcc
	s_cbranch_execz .LBB0_509
	s_bcnt1_i32_b64 s3, s[12:13]
	v_mov_b32_e32 v1, 0x2000
	v_mov_b32_e32 v2, s3
	global_atomic_add v1, v2, s[8:9] offset:1024

.LBB0_529:
	s_andn2_b64 vcc, exec, s[12:13]
	s_cbranch_vccnz .LBB0_597
	v_ashrrev_i32_e32 v1, 31, v10
	v_lshrrev_b32_e32 v1, 26, v1
	v_add_u32_e32 v1, v10, v1
	v_ashrrev_i32_e32 v2, 6, v1
	v_bfe_i32 v1, v10, 27, 1
	s_waitcnt lgkmcnt(0)
	v_lshlrev_b32_e32 v3, 4, v10
	v_lshrrev_b32_e32 v1, 22, v1
	v_add_u32_e32 v1, v3, v1
	v_and_b32_e32 v1, 0xfffffc00, v1
	v_sub_u32_e32 v1, v3, v1
	v_lshrrev_b32_e32 v4, 4, v1
	v_bitop3_b32 v4, v4, v1, 32 bitop3:0x6c
	v_readlane_b32 s6, v236, 6
	v_ashrrev_i32_e32 v5, 31, v4
	s_add_u32 s3, s72, 0xe00000
	v_readlane_b32 s7, v236, 7
	v_readlane_b32 s5, v236, 8
	v_lshrrev_b32_e32 v5, 26, v5
	s_addc_u32 s4, s73, 0
	s_and_b64 s[10:11], s[6:7], s[10:11]
	s_lshl_b32 s5, s5, 6
	v_add_u32_e32 v5, v4, v5
	s_add_u32 s5, s72, s5
	v_ashrrev_i32_e32 v6, 6, v5
	v_and_b32_e32 v5, 0xc0, v5
	s_addc_u32 s6, s73, 0
	v_sub_u32_e32 v4, v4, v5
	v_mov_b32_e32 v5, 1
	s_add_u32 s5, s5, 0x93000
	v_lshlrev_b32_e32 v1, 3, v2
	v_lshlrev_b32_e32 v2, 5, v2
	v_ashrrev_i16_sdwa v4, v5, sext(v4) dst_sel:DWORD dst_unused:UNUSED_PAD src0_sel:DWORD src1_sel:BYTE_0
	s_addc_u32 s12, s6, 0
	v_and_b32_e32 v1, -16, v1
	v_and_b32_e32 v2, 32, v2
	v_bfe_i32 v4, v4, 0, 16
	v_add_u32_e32 v3, 0x2000, v3
	s_and_b64 s[6:7], s[10:11], exec
	v_add_u32_e32 v1, v6, v1
	v_add_lshl_u32 v2, v2, v4, 1
	v_ashrrev_i32_e32 v4, 31, v3
	s_cselect_b32 s13, s12, 0
	s_cselect_b32 s12, s5, 0
	v_lshlrev_b32_e32 v7, 1, v1
	v_lshrrev_b32_e32 v8, 2, v1
	v_and_b32_e32 v6, 3, v6
	s_mov_b32 s5, 0x1fffe0
	v_lshrrev_b32_e32 v4, 22, v4
	v_and_b32_e32 v7, 24, v7
	v_and_b32_e32 v8, 4, v8
	v_and_or_b32 v6, v1, s5, v6
	v_add_u32_e32 v4, v3, v4
	v_or3_b32 v6, v6, v8, v7
	v_ashrrev_i32_e32 v4, 10, v4
	v_lshl_add_u32 v154, v6, 11, v2
	v_mul_i32_i24_e32 v6, 0x400, v4
	v_sub_u32_e32 v3, v3, v6
	v_lshrrev_b32_e32 v6, 4, v3
	v_bitop3_b32 v6, v6, v3, 32 bitop3:0x6c
	v_ashrrev_i32_e32 v7, 31, v6
	v_lshrrev_b32_e32 v7, 26, v7
	v_lshlrev_b32_e32 v3, 3, v4
	v_add_u32_e32 v7, v6, v7
	v_and_b32_e32 v3, -16, v3
	v_ashrrev_i32_e32 v8, 6, v7
	v_add_u32_e32 v3, v8, v3
	v_and_b32_e32 v8, 3, v8
	s_ashr_i32 s20, s24, 6
	s_ashr_i32 s43, s42, 31
	v_and_b32_e32 v7, 0xc0, v7
	v_and_or_b32 v8, v3, s5, v8
	s_lshl_b32 s5, s20, 10
	s_lshl_b64 s[6:7], s[42:43], 19
	v_sub_u32_e32 v6, v6, v7
	s_add_u32 s44, s3, s6
	v_lshlrev_b32_e32 v4, 5, v4
	v_ashrrev_i16_sdwa v5, v5, sext(v6) dst_sel:DWORD dst_unused:UNUSED_PAD src0_sel:DWORD src1_sel:BYTE_0
	v_lshlrev_b32_e32 v6, 1, v3
	v_lshrrev_b32_e32 v7, 2, v3
	s_addc_u32 s45, s4, s7
	s_add_i32 s33, s5, 0
	v_and_b32_e32 v4, 32, v4
	v_bfe_i32 v5, v5, 0, 16
	v_and_b32_e32 v6, 24, v6
	v_and_b32_e32 v7, 4, v7
	s_add_i32 m0, s33, 0x10000
	v_or3_b32 v6, v8, v7, v6
	v_add_lshl_u32 v4, v4, v5, 1
	global_load_lds_dwordx4 v154, s[44:45]
	s_add_i32 m0, s33, 0x12000
	v_lshl_add_u32 v156, v6, 11, v4
	s_add_u32 s6, s44, 0x40000
	global_load_lds_dwordx4 v156, s[44:45]
	s_addc_u32 s7, s45, 0
	s_add_i32 m0, s33, 0x14000
	v_mov_b32_e32 v159, 0
	global_load_lds_dwordx4 v154, s[6:7]
	s_add_i32 m0, s33, 0x16000
	s_cmp_eq_u32 s42, s84
	global_load_lds_dwordx4 v156, s[6:7]
	s_cselect_b64 s[6:7], -1, 0
	s_and_b64 s[6:7], s[10:11], s[6:7]
	v_mov_b32_e32 v155, v159
	s_andn2_b64 vcc, exec, s[6:7]
	v_mov_b32_e32 v157, v159
	s_cbranch_vccnz .LBB0_545
	s_and_saveexec_b64 s[6:7], s[22:23]
	s_cbranch_execz .LBB0_544
	s_mov_b32 s16, 0x400001
	buffer_inv sc1
	v_mov_b32_e32 v5, 0
	s_branch .LBB0_534

.LBB0_542:
	s_ashr_i32 s3, s3, 3
	s_add_i32 s3, s5, s3
	s_ashr_i32 s4, s3, 31
	s_lshr_b32 s4, s4, 27
	s_add_i32 s4, s3, s4
	s_ashr_i32 s5, s4, 5
	s_andn2_b32 s4, s4, 31
	s_sub_i32 s3, s3, s4
	s_bfe_i32 s4, s3, 0x80000
	s_bfe_u32 s4, s4, 0x3000c
	s_add_i32 s4, s3, s4
	s_bfe_i32 s12, s4, 0x80000
	s_and_b32 s4, s4, 0xf8
	s_sub_i32 s3, s3, s4
	s_lshl_b32 s5, s5, 3
	s_sext_i32_i8 s3, s3
	s_sext_i32_i16 s12, s12
	s_waitcnt lgkmcnt(0)
	s_add_i32 s40, s5, s3
	v_readlane_b32 s4, v236, 4
	s_ashr_i32 s42, s12, 3
	s_mov_b64 s[12:13], -1
	v_readlane_b32 s5, v236, 5
	s_andn2_b64 vcc, exec, s[6:7]
	s_cbranch_vccz .LBB0_525
	s_branch .LBB0_529
.LBB0_543:
	s_waitcnt lgkmcnt(0)
	s_waitcnt vmcnt(0)
.LBB0_544:
	s_or_b64 exec, exec, s[6:7]
	s_barrier

.LBB0_617:
	s_or_b64 exec, exec, s[14:15]
	v_cvt_f32_u32_e32 v5, v3
	s_waitcnt vmcnt(0)
	v_readfirstlane_b32 s3, v4
	v_sub_u32_e32 v4, 0, v3
	v_rcp_iflag_f32_e32 v5, v5
	v_add_u32_e32 v6, s3, v2
	v_mul_f32_e32 v5, 0x4f7ffffe, v5
	v_cvt_u32_f32_e32 v5, v5
	v_mul_lo_u32 v2, v4, v5
	v_mul_hi_u32 v2, v5, v2
	v_add_u32_e32 v2, v5, v2
	v_mul_hi_u32 v2, v6, v2
	v_mul_lo_u32 v4, v2, v3
	v_sub_u32_e32 v4, v6, v4
	v_add_u32_e32 v5, 1, v2
	v_cmp_ge_u32_e32 vcc, v4, v3
	s_nop 1
	v_cndmask_b32_e32 v2, v2, v5, vcc
	v_sub_u32_e32 v5, v4, v3
	v_cndmask_b32_e32 v4, v4, v5, vcc
	v_add_u32_e32 v5, 1, v2
	v_cmp_ge_u32_e32 vcc, v4, v3
	v_add_u32_e32 v4, 1, v6
	s_nop 0
	v_cndmask_b32_e32 v2, v2, v5, vcc
	v_mul_lo_u32 v5, v3, v2
	v_add_u32_e32 v3, v5, v3
	v_cmp_ne_u32_e32 vcc, v4, v3
	s_and_saveexec_b64 s[4:5], vcc
	s_xor_b64 s[12:13], exec, s[4:5]
	s_cbranch_execz .LBB0_631
	s_waitcnt lgkmcnt(0)
	buffer_inv sc1
	v_mov_b32_e32 v1, 0x2000
	global_load_dword v1, v1, s[10:11] offset:1024 sc1
	s_add_u32 s18, s10, 0x2400
	s_addc_u32 s19, s11, 0
	s_waitcnt vmcnt(0)
	v_cmp_eq_u32_e32 vcc, v1, v2
	s_and_saveexec_b64 s[14:15], vcc
	s_cbranch_execz .LBB0_630
	s_add_u32 s16, s72, 0x4200
	s_addc_u32 s17, s73, 0
	s_mov_b32 s3, 1
	s_mov_b64 s[20:21], 0
	v_mov_b32_e32 v1, 0
	s_branch .LBB0_621

.LBB0_648:
	s_or_b64 exec, exec, s[12:13]
	s_mov_b64 s[12:13], exec
	v_mbcnt_lo_u32_b32 v1, s12, 0
	v_mbcnt_hi_u32_b32 v1, s13, v1
	v_cmp_eq_u32_e32 vcc, 0, v1
	s_waitcnt vmcnt(0)
	s_and_saveexec_b64 s[14:15], vcc
	s_cbranch_execz .LBB0_650
	s_bcnt1_i32_b64 s3, s[12:13]
	v_mov_b32_e32 v1, 0x2000
	v_mov_b32_e32 v2, s3
	global_atomic_add v1, v2, s[10:11] offset:1024

.LBB0_669:
	s_andn2_b64 vcc, exec, s[12:13]
	s_cbranch_vccnz .LBB0_718
	v_ashrrev_i32_e32 v1, 31, v10
	v_lshrrev_b32_e32 v1, 26, v1
	v_add_u32_e32 v1, v10, v1
	v_ashrrev_i32_e32 v2, 6, v1
	v_bfe_i32 v1, v10, 27, 1
	s_waitcnt lgkmcnt(0)
	v_lshlrev_b32_e32 v3, 4, v10
	v_lshrrev_b32_e32 v1, 22, v1
	v_add_u32_e32 v1, v3, v1
	v_and_b32_e32 v1, 0xfffffc00, v1
	v_sub_u32_e32 v1, v3, v1
	v_lshrrev_b32_e32 v4, 4, v1
	v_readlane_b32 s10, v236, 6
	v_bitop3_b32 v4, v4, v1, 32 bitop3:0x6c
	s_add_u32 s3, s72, 0x1700000
	v_readlane_b32 s11, v236, 7
	v_ashrrev_i32_e32 v5, 31, v4
	s_addc_u32 s4, s73, 0
	s_and_b64 s[24:25], s[10:11], s[0:1]
	v_readlane_b32 s0, v236, 8
	v_lshrrev_b32_e32 v5, 26, v5
	s_lshl_b32 s0, s0, 6
	v_add_u32_e32 v5, v4, v5
	s_add_u32 s0, s72, s0
	v_ashrrev_i32_e32 v6, 6, v5
	v_and_b32_e32 v5, 0xc0, v5
	s_addc_u32 s1, s73, 0
	v_sub_u32_e32 v4, v4, v5
	v_mov_b32_e32 v5, 1
	s_add_u32 s5, s0, 0x94000
	v_lshlrev_b32_e32 v1, 3, v2
	v_lshlrev_b32_e32 v2, 5, v2
	v_ashrrev_i16_sdwa v4, v5, sext(v4) dst_sel:DWORD dst_unused:UNUSED_PAD src0_sel:DWORD src1_sel:BYTE_0
	s_addc_u32 s7, s1, 0
	v_and_b32_e32 v1, -16, v1
	v_and_b32_e32 v2, 32, v2
	v_bfe_i32 v4, v4, 0, 16
	v_add_u32_e32 v3, 0x2000, v3
	s_and_b64 s[0:1], s[24:25], exec
	v_add_u32_e32 v1, v6, v1
	v_add_lshl_u32 v2, v2, v4, 1
	v_ashrrev_i32_e32 v4, 31, v3
	v_lshlrev_b32_e32 v7, 1, v1
	v_lshrrev_b32_e32 v8, 2, v1
	v_and_b32_e32 v6, 3, v6
	s_mov_b32 s0, 0x1fffe0
	v_lshrrev_b32_e32 v4, 22, v4
	v_and_b32_e32 v7, 24, v7
	v_and_b32_e32 v8, 4, v8
	v_and_or_b32 v6, v1, s0, v6
	v_add_u32_e32 v4, v3, v4
	v_or3_b32 v6, v6, v8, v7
	v_ashrrev_i32_e32 v4, 10, v4
	v_lshl_add_u32 v130, v6, 11, v2
	v_mul_i32_i24_e32 v6, 0x400, v4
	v_sub_u32_e32 v3, v3, v6
	v_lshrrev_b32_e32 v6, 4, v3
	v_bitop3_b32 v6, v6, v3, 32 bitop3:0x6c
	v_ashrrev_i32_e32 v7, 31, v6
	v_lshrrev_b32_e32 v7, 26, v7
	v_lshlrev_b32_e32 v3, 3, v4
	v_add_u32_e32 v7, v6, v7
	v_and_b32_e32 v3, -16, v3
	v_ashrrev_i32_e32 v8, 6, v7
	s_cselect_b32 s27, s7, 0
	s_cselect_b32 s26, s5, 0
	v_add_u32_e32 v3, v8, v3
	v_and_b32_e32 v8, 3, v8
	s_ashr_i32 s15, s14, 6
	s_ashr_i32 s7, s6, 31
	v_and_b32_e32 v7, 0xc0, v7
	v_and_or_b32 v8, v3, s0, v8
	s_lshl_b32 s5, s15, 10
	s_lshl_b64 s[0:1], s[6:7], 19
	v_sub_u32_e32 v6, v6, v7
	s_add_u32 s0, s3, s0
	v_lshlrev_b32_e32 v4, 5, v4
	v_ashrrev_i16_sdwa v5, v5, sext(v6) dst_sel:DWORD dst_unused:UNUSED_PAD src0_sel:DWORD src1_sel:BYTE_0
	v_lshlrev_b32_e32 v6, 1, v3
	v_lshrrev_b32_e32 v7, 2, v3
	s_addc_u32 s1, s4, s1
	s_add_i32 s33, s5, 0
	v_and_b32_e32 v4, 32, v4
	v_bfe_i32 v5, v5, 0, 16
	v_and_b32_e32 v6, 24, v6
	v_and_b32_e32 v7, 4, v7
	s_add_i32 m0, s33, 0x10000
	v_or3_b32 v6, v8, v7, v6
	v_add_lshl_u32 v4, v4, v5, 1
	global_load_lds_dwordx4 v130, s[0:1]
	s_add_i32 m0, s33, 0x12000
	v_lshl_add_u32 v132, v6, 11, v4
	s_add_u32 s10, s0, 0x40000
	global_load_lds_dwordx4 v132, s[0:1]
	s_addc_u32 s11, s1, 0
	s_add_i32 m0, s33, 0x14000
	v_mov_b32_e32 v135, 0
	global_load_lds_dwordx4 v130, s[10:11]
	s_add_i32 m0, s33, 0x16000
	s_cmp_eq_u32 s6, s84
	global_load_lds_dwordx4 v132, s[10:11]
	s_cselect_b64 s[10:11], -1, 0
	s_and_b64 s[10:11], s[24:25], s[10:11]
	v_mov_b32_e32 v131, v135
	s_andn2_b64 vcc, exec, s[10:11]
	v_mov_b32_e32 v133, v135
	s_cbranch_vccnz .LBB0_682
	s_and_saveexec_b64 s[10:11], s[22:23]
	s_cbranch_execz .LBB0_681
	s_mov_b32 s7, 0x400001
	buffer_inv sc1
	v_mov_b32_e32 v5, 0
	s_branch .LBB0_674

.LBB0_674:
	global_load_dword v6, v5, s[26:27] sc1
	s_mov_b64 s[12:13], -1
	s_waitcnt vmcnt(0)
	v_cmp_lt_u32_e32 vcc, 3, v6
	s_cbranch_vccnz .LBB0_673
	s_sleep 1
	global_load_dword v6, v5, s[26:27] sc1
	s_waitcnt vmcnt(0)
	v_cmp_gt_u32_e32 vcc, 4, v6
	s_cbranch_vccz .LBB0_673
	s_sleep 1
	global_load_dword v6, v5, s[26:27] sc1
	s_waitcnt vmcnt(0)
	v_cmp_gt_u32_e32 vcc, 4, v6
	s_cbranch_vccz .LBB0_673
	s_sleep 1
	global_load_dword v6, v5, s[26:27] sc1
	s_waitcnt vmcnt(0)
	v_cmp_gt_u32_e32 vcc, 4, v6
	s_cbranch_vccz .LBB0_673
	s_sleep 1
	global_load_dword v6, v5, s[26:27] sc1
	s_waitcnt vmcnt(0)
	v_cmp_gt_u32_e32 vcc, 4, v6
	s_cbranch_vccz .LBB0_673
	s_add_i32 s7, s7, -5
	s_cmp_eq_u32 s7, 0
	s_cselect_b64 s[12:13], -1, 0
	s_sleep 1
	s_branch .LBB0_673
.LBB0_680:
	s_waitcnt lgkmcnt(0)
	s_waitcnt vmcnt(0)
.LBB0_681:
	s_or_b64 exec, exec, s[10:11]
	s_barrier

.LBB0_738:
	s_or_b64 exec, exec, s[12:13]
	v_cvt_f32_u32_e32 v5, v3
	s_waitcnt vmcnt(0)
	v_readfirstlane_b32 s3, v4
	v_sub_u32_e32 v4, 0, v3
	v_rcp_iflag_f32_e32 v5, v5
	v_add_u32_e32 v6, s3, v2
	v_mul_f32_e32 v5, 0x4f7ffffe, v5
	v_cvt_u32_f32_e32 v5, v5
	v_mul_lo_u32 v2, v4, v5
	v_mul_hi_u32 v2, v5, v2
	v_add_u32_e32 v2, v5, v2
	v_mul_hi_u32 v2, v6, v2
	v_mul_lo_u32 v4, v2, v3
	v_sub_u32_e32 v4, v6, v4
	v_add_u32_e32 v5, 1, v2
	v_cmp_ge_u32_e32 vcc, v4, v3
	s_nop 1
	v_cndmask_b32_e32 v2, v2, v5, vcc
	v_sub_u32_e32 v5, v4, v3
	v_cndmask_b32_e32 v4, v4, v5, vcc
	v_add_u32_e32 v5, 1, v2
	v_cmp_ge_u32_e32 vcc, v4, v3
	v_add_u32_e32 v4, 1, v6
	s_nop 0
	v_cndmask_b32_e32 v2, v2, v5, vcc
	v_mul_lo_u32 v5, v3, v2
	v_add_u32_e32 v3, v5, v3
	v_cmp_ne_u32_e32 vcc, v4, v3
	s_and_saveexec_b64 s[4:5], vcc
	s_xor_b64 s[10:11], exec, s[4:5]
	s_cbranch_execz .LBB0_752
	s_waitcnt lgkmcnt(0)
	buffer_inv sc1
	v_mov_b32_e32 v1, 0x2000
	global_load_dword v1, v1, s[8:9] offset:1024 sc1
	s_add_u32 s16, s8, 0x2400
	s_addc_u32 s17, s9, 0
	s_waitcnt vmcnt(0)
	v_cmp_eq_u32_e32 vcc, v1, v2
	s_and_saveexec_b64 s[12:13], vcc
	s_cbranch_execz .LBB0_751
	s_add_u32 s14, s72, 0x4200
	s_addc_u32 s15, s73, 0
	s_mov_b32 s3, 1
	s_mov_b64 s[20:21], 0
	v_mov_b32_e32 v1, 0
	s_branch .LBB0_742

.LBB0_791:
	s_andn2_b64 vcc, exec, s[8:9]
	s_cbranch_vccnz .LBB0_859
	v_ashrrev_i32_e32 v1, 31, v10
	v_lshrrev_b32_e32 v1, 26, v1
	v_add_u32_e32 v1, v10, v1
	v_ashrrev_i32_e32 v2, 6, v1
	v_bfe_i32 v1, v10, 27, 1
	s_waitcnt lgkmcnt(0)
	v_lshlrev_b32_e32 v3, 4, v10
	v_lshrrev_b32_e32 v1, 22, v1
	v_add_u32_e32 v1, v3, v1
	v_and_b32_e32 v1, 0xfffffc00, v1
	v_sub_u32_e32 v1, v3, v1
	v_lshrrev_b32_e32 v4, 4, v1
	v_bitop3_b32 v4, v4, v1, 32 bitop3:0x6c
	v_readlane_b32 s6, v236, 6
	v_ashrrev_i32_e32 v5, 31, v4
	s_add_u32 s3, s72, 0x2700000
	v_readlane_b32 s7, v236, 7
	v_readlane_b32 s5, v236, 8
	v_lshrrev_b32_e32 v5, 26, v5
	s_addc_u32 s4, s73, 0
	s_and_b64 s[8:9], s[6:7], s[18:19]
	s_lshl_b32 s5, s5, 6
	v_add_u32_e32 v5, v4, v5
	s_add_u32 s5, s72, s5
	v_ashrrev_i32_e32 v6, 6, v5
	v_and_b32_e32 v5, 0xc0, v5
	s_addc_u32 s6, s73, 0
	v_sub_u32_e32 v4, v4, v5
	v_mov_b32_e32 v5, 1
	s_add_u32 s5, s5, 0x95000
	v_lshlrev_b32_e32 v1, 3, v2
	v_lshlrev_b32_e32 v2, 5, v2
	v_ashrrev_i16_sdwa v4, v5, sext(v4) dst_sel:DWORD dst_unused:UNUSED_PAD src0_sel:DWORD src1_sel:BYTE_0
	s_addc_u32 s10, s6, 0
	v_and_b32_e32 v1, -16, v1
	v_and_b32_e32 v2, 32, v2
	v_bfe_i32 v4, v4, 0, 16
	v_add_u32_e32 v3, 0x2000, v3
	s_and_b64 s[6:7], s[8:9], exec
	v_add_u32_e32 v1, v6, v1
	v_add_lshl_u32 v2, v2, v4, 1
	v_ashrrev_i32_e32 v4, 31, v3
	s_cselect_b32 s11, s10, 0
	s_cselect_b32 s10, s5, 0
	v_lshlrev_b32_e32 v7, 1, v1
	v_lshrrev_b32_e32 v8, 2, v1
	v_and_b32_e32 v6, 3, v6
	s_mov_b32 s5, 0x7ffe0
	v_lshrrev_b32_e32 v4, 22, v4
	v_and_b32_e32 v7, 24, v7
	v_and_b32_e32 v8, 4, v8
	v_and_or_b32 v6, v1, s5, v6
	v_add_u32_e32 v4, v3, v4
	v_or3_b32 v6, v6, v8, v7
	v_ashrrev_i32_e32 v4, 10, v4
	v_lshl_add_u32 v154, v6, 13, v2
	v_mul_i32_i24_e32 v6, 0x400, v4
	v_sub_u32_e32 v3, v3, v6
	v_lshrrev_b32_e32 v6, 4, v3
	v_bitop3_b32 v6, v6, v3, 32 bitop3:0x6c
	v_ashrrev_i32_e32 v7, 31, v6
	v_lshrrev_b32_e32 v7, 26, v7
	v_lshlrev_b32_e32 v3, 3, v4
	v_add_u32_e32 v7, v6, v7
	v_and_b32_e32 v3, -16, v3
	v_ashrrev_i32_e32 v8, 6, v7
	v_add_u32_e32 v3, v8, v3
	v_and_b32_e32 v8, 3, v8
	s_ashr_i32 s18, s20, 6
	s_ashr_i32 s41, s40, 31
	v_and_b32_e32 v7, 0xc0, v7
	v_and_or_b32 v8, v3, s5, v8
	s_lshl_b32 s5, s18, 10
	s_lshl_b64 s[6:7], s[40:41], 21
	v_sub_u32_e32 v6, v6, v7
	s_add_u32 s42, s3, s6
	v_lshlrev_b32_e32 v4, 5, v4
	v_ashrrev_i16_sdwa v5, v5, sext(v6) dst_sel:DWORD dst_unused:UNUSED_PAD src0_sel:DWORD src1_sel:BYTE_0
	v_lshlrev_b32_e32 v6, 1, v3
	v_lshrrev_b32_e32 v7, 2, v3
	s_addc_u32 s43, s4, s7
	s_add_i32 s33, s5, 0
	v_and_b32_e32 v4, 32, v4
	v_bfe_i32 v5, v5, 0, 16
	v_and_b32_e32 v6, 24, v6
	v_and_b32_e32 v7, 4, v7
	s_add_i32 m0, s33, 0x10000
	v_or3_b32 v6, v8, v7, v6
	v_add_lshl_u32 v4, v4, v5, 1
	global_load_lds_dwordx4 v154, s[42:43]
	s_add_i32 m0, s33, 0x12000
	v_lshl_add_u32 v156, v6, 13, v4
	s_add_u32 s6, s42, 0x100000
	global_load_lds_dwordx4 v156, s[42:43]
	s_addc_u32 s7, s43, 0
	s_add_i32 m0, s33, 0x14000
	v_mov_b32_e32 v159, 0
	global_load_lds_dwordx4 v154, s[6:7]
	s_add_i32 m0, s33, 0x16000
	s_cmp_eq_u32 s40, s84
	global_load_lds_dwordx4 v156, s[6:7]
	s_cselect_b64 s[6:7], -1, 0
	s_and_b64 s[6:7], s[8:9], s[6:7]
	v_mov_b32_e32 v155, v159
	s_andn2_b64 vcc, exec, s[6:7]
	v_mov_b32_e32 v157, v159
	s_cbranch_vccnz .LBB0_807
	s_and_saveexec_b64 s[6:7], s[22:23]
	s_cbranch_execz .LBB0_806
	s_mov_b32 s14, 0x400001
	buffer_inv sc1
	v_mov_b32_e32 v5, 0
	s_branch .LBB0_796

.LBB0_804:
	s_ashr_i32 s3, s3, 3
	s_add_i32 s3, s5, s3
	s_ashr_i32 s4, s3, 31
	s_lshr_b32 s4, s4, 27
	s_add_i32 s4, s3, s4
	s_ashr_i32 s5, s4, 5
	s_andn2_b32 s4, s4, 31
	s_sub_i32 s3, s3, s4
	s_bfe_i32 s4, s3, 0x80000
	s_bfe_u32 s4, s4, 0x3000c
	s_add_i32 s4, s3, s4
	s_bfe_i32 s8, s4, 0x80000
	s_and_b32 s4, s4, 0xf8
	s_sub_i32 s3, s3, s4
	s_lshl_b32 s5, s5, 3
	s_sext_i32_i16 s8, s8
	s_sext_i32_i8 s3, s3
	s_waitcnt lgkmcnt(0)
	s_add_i32 s38, s5, s3
	s_ashr_i32 s40, s8, 3
	s_mov_b64 s[8:9], -1
	s_andn2_b64 vcc, exec, s[6:7]
	s_cbranch_vccz .LBB0_787
	s_branch .LBB0_791
.LBB0_805:
	s_waitcnt lgkmcnt(0)
	s_waitcnt vmcnt(0)
.LBB0_806:
	s_or_b64 exec, exec, s[6:7]
	s_barrier

.LBB0_920:
	s_or_b64 exec, exec, s[12:13]
	s_mov_b32 s3, 0x400001
	buffer_inv sc1
	v_mov_b32_e32 v1, 0
	s_branch .LBB0_922

.LBB0_922:
	global_load_dword v2, v1, s[8:9] sc1
	s_mov_b64 s[10:11], -1
	s_waitcnt vmcnt(0)
	v_cmp_lt_u32_e32 vcc, 3, v2
	s_cbranch_vccnz .LBB0_921
	s_sleep 1
	global_load_dword v2, v1, s[8:9] sc1
	s_waitcnt vmcnt(0)
	v_cmp_gt_u32_e32 vcc, 4, v2
	s_cbranch_vccz .LBB0_921
	s_sleep 1
	global_load_dword v2, v1, s[8:9] sc1
	s_waitcnt vmcnt(0)
	v_cmp_gt_u32_e32 vcc, 4, v2
	s_cbranch_vccz .LBB0_921
	s_sleep 1
	global_load_dword v2, v1, s[8:9] sc1
	s_waitcnt vmcnt(0)
	v_cmp_gt_u32_e32 vcc, 4, v2
	s_cbranch_vccz .LBB0_921
	s_sleep 1
	global_load_dword v2, v1, s[8:9] sc1
	s_waitcnt vmcnt(0)
	v_cmp_gt_u32_e32 vcc, 4, v2
	s_cbranch_vccz .LBB0_921
	s_add_i32 s3, s3, -5
	s_cmp_eq_u32 s3, 0
	s_cselect_b64 s[10:11], -1, 0
	s_sleep 1
	s_branch .LBB0_921
.LBB0_928:
	s_waitcnt vmcnt(0)
.LBB0_929:
	s_or_b64 exec, exec, s[0:1]
	v_readlane_b32 s4, v236, 4
	s_barrier
	v_readlane_b32 s5, v236, 5

.LBB0_1257:
	global_load_dword v2, v1, s[8:9] sc1
	s_mov_b64 s[10:11], -1
	s_waitcnt vmcnt(0)
	v_cmp_lt_u32_e32 vcc, 3, v2
	s_cbranch_vccnz .LBB0_1256
	s_sleep 1
	global_load_dword v2, v1, s[8:9] sc1
	s_waitcnt vmcnt(0)
	v_cmp_gt_u32_e32 vcc, 4, v2
	s_cbranch_vccz .LBB0_1256
	s_sleep 1
	global_load_dword v2, v1, s[8:9] sc1
	s_waitcnt vmcnt(0)
	v_cmp_gt_u32_e32 vcc, 4, v2
	s_cbranch_vccz .LBB0_1256
	s_sleep 1
	global_load_dword v2, v1, s[8:9] sc1
	s_waitcnt vmcnt(0)
	v_cmp_gt_u32_e32 vcc, 4, v2
	s_cbranch_vccz .LBB0_1256
	s_sleep 1
	global_load_dword v2, v1, s[8:9] sc1
	s_waitcnt vmcnt(0)
	v_cmp_gt_u32_e32 vcc, 4, v2
	s_cbranch_vccz .LBB0_1256
	s_add_i32 s3, s3, -5
	s_cmp_eq_u32 s3, 0
	s_cselect_b64 s[10:11], -1, 0
	s_sleep 1
	s_branch .LBB0_1256
.LBB0_1263:
	s_waitcnt vmcnt(0)
.LBB0_1264:
	s_or_b64 exec, exec, s[0:1]
	v_readlane_b32 s4, v236, 4
	s_barrier
	v_readlane_b32 s5, v236, 5

.LBB0_1612:
	s_or_b64 exec, exec, s[12:13]
	v_cvt_f32_u32_e32 v4, v2
	s_waitcnt vmcnt(0)
	v_readfirstlane_b32 s3, v3
	v_sub_u32_e32 v3, 0, v2
	v_rcp_iflag_f32_e32 v4, v4
	v_add_u32_e32 v5, s3, v1
	v_mul_f32_e32 v4, 0x4f7ffffe, v4
	v_cvt_u32_f32_e32 v4, v4
	v_mul_lo_u32 v1, v3, v4
	v_mul_hi_u32 v1, v4, v1
	v_add_u32_e32 v1, v4, v1
	v_mul_hi_u32 v1, v5, v1
	v_mul_lo_u32 v3, v1, v2
	v_sub_u32_e32 v3, v5, v3
	v_add_u32_e32 v4, 1, v1
	v_cmp_ge_u32_e32 vcc, v3, v2
	s_nop 1
	v_cndmask_b32_e32 v1, v1, v4, vcc
	v_sub_u32_e32 v4, v3, v2
	v_cndmask_b32_e32 v3, v3, v4, vcc
	v_add_u32_e32 v4, 1, v1
	v_cmp_ge_u32_e32 vcc, v3, v2
	v_add_u32_e32 v3, 1, v5
	s_nop 0
	v_cndmask_b32_e32 v1, v1, v4, vcc
	v_mul_lo_u32 v4, v2, v1
	v_add_u32_e32 v2, v4, v2
	v_cmp_ne_u32_e32 vcc, v3, v2
	s_and_saveexec_b64 s[4:5], vcc
	s_xor_b64 s[10:11], exec, s[4:5]
	s_cbranch_execz .LBB0_1626
	s_waitcnt lgkmcnt(0)
	buffer_inv sc1
	v_mov_b32_e32 v0, 0x2000
	global_load_dword v0, v0, s[8:9] offset:1024 sc1
	s_add_u32 s16, s8, 0x2400
	s_addc_u32 s17, s9, 0
	s_waitcnt vmcnt(0)
	v_cmp_eq_u32_e32 vcc, v0, v1
	s_and_saveexec_b64 s[12:13], vcc
	s_cbranch_execz .LBB0_1625
	s_add_u32 s14, s72, 0x4200
	s_addc_u32 s15, s73, 0
	s_mov_b32 s3, 1
	s_mov_b64 s[18:19], 0
	v_mov_b32_e32 v0, 0
	s_branch .LBB0_1616

.LBB0_1626:
	s_andn2_saveexec_b64 s[4:5], s[10:11]
	s_cbranch_execz .LBB0_1646
	s_mov_b64 s[10:11], exec
	buffer_wbl2 sc1
	s_waitcnt lgkmcnt(0)
	s_waitcnt vmcnt(0)
	buffer_inv sc1
	v_mbcnt_lo_u32_b32 v1, s10, 0
	v_mbcnt_hi_u32_b32 v1, s11, v1
	v_cmp_eq_u32_e32 vcc, 0, v1
	s_and_saveexec_b64 s[12:13], vcc
	s_cbranch_execz .LBB0_1629
	s_bcnt1_i32_b64 s3, s[10:11]
	v_mov_b32_e32 v2, 0x7000
	v_mov_b32_e32 v3, s3
	global_atomic_add v2, v2, v3, s[72:73] offset:1024 sc0

.LBB0_1643:
	s_or_b64 exec, exec, s[10:11]
	s_mov_b64 s[10:11], exec
	v_mbcnt_lo_u32_b32 v0, s10, 0
	v_mbcnt_hi_u32_b32 v0, s11, v0
	v_cmp_eq_u32_e32 vcc, 0, v0
	s_waitcnt vmcnt(0)
	s_and_saveexec_b64 s[12:13], vcc
	s_cbranch_execz .LBB0_1645
	s_bcnt1_i32_b64 s3, s[10:11]
	v_mov_b32_e32 v0, 0x2000
	v_mov_b32_e32 v1, s3
	global_atomic_add v0, v1, s[8:9] offset:1024

.LBB0_1722:
	s_or_b64 exec, exec, s[14:15]
	v_cvt_f32_u32_e32 v4, v2
	s_waitcnt vmcnt(0)
	v_readfirstlane_b32 s3, v3
	v_sub_u32_e32 v3, 0, v2
	v_rcp_iflag_f32_e32 v4, v4
	v_add_u32_e32 v5, s3, v1
	v_mul_f32_e32 v4, 0x4f7ffffe, v4
	v_cvt_u32_f32_e32 v4, v4
	v_mul_lo_u32 v1, v3, v4
	v_mul_hi_u32 v1, v4, v1
	v_add_u32_e32 v1, v4, v1
	v_mul_hi_u32 v1, v5, v1
	v_mul_lo_u32 v3, v1, v2
	v_sub_u32_e32 v3, v5, v3
	v_add_u32_e32 v4, 1, v1
	v_cmp_ge_u32_e32 vcc, v3, v2
	s_nop 1
	v_cndmask_b32_e32 v1, v1, v4, vcc
	v_sub_u32_e32 v4, v3, v2
	v_cndmask_b32_e32 v3, v3, v4, vcc
	v_add_u32_e32 v4, 1, v1
	v_cmp_ge_u32_e32 vcc, v3, v2
	v_add_u32_e32 v3, 1, v5
	s_nop 0
	v_cndmask_b32_e32 v1, v1, v4, vcc
	v_mul_lo_u32 v4, v2, v1
	v_add_u32_e32 v2, v4, v2
	v_cmp_ne_u32_e32 vcc, v3, v2
	s_and_saveexec_b64 s[4:5], vcc
	s_xor_b64 s[12:13], exec, s[4:5]
	s_cbranch_execz .LBB0_1736
	s_waitcnt lgkmcnt(0)
	buffer_inv sc1
	v_mov_b32_e32 v0, 0x2000
	global_load_dword v0, v0, s[10:11] offset:1024 sc1
	s_add_u32 s18, s10, 0x2400
	s_addc_u32 s19, s11, 0
	s_waitcnt vmcnt(0)
	v_cmp_eq_u32_e32 vcc, v0, v1
	s_and_saveexec_b64 s[14:15], vcc
	s_cbranch_execz .LBB0_1735
	s_add_u32 s16, s72, 0x4200
	s_addc_u32 s17, s73, 0
	s_mov_b32 s3, 1
	s_mov_b64 s[20:21], 0
	v_mov_b32_e32 v0, 0
	s_branch .LBB0_1726

.LBB0_1736:
	s_andn2_saveexec_b64 s[4:5], s[12:13]
	s_cbranch_execz .LBB0_1756
	s_mov_b64 s[12:13], exec
	buffer_wbl2 sc1
	s_waitcnt lgkmcnt(0)
	s_waitcnt vmcnt(0)
	buffer_inv sc1
	v_mbcnt_lo_u32_b32 v1, s12, 0
	v_mbcnt_hi_u32_b32 v1, s13, v1
	v_cmp_eq_u32_e32 vcc, 0, v1
	s_and_saveexec_b64 s[14:15], vcc
	s_cbranch_execz .LBB0_1739
	s_bcnt1_i32_b64 s3, s[12:13]
	v_mov_b32_e32 v2, 0x7000
	v_mov_b32_e32 v3, s3
	global_atomic_add v2, v2, v3, s[72:73] offset:1024 sc0

.LBB0_1753:
	s_or_b64 exec, exec, s[12:13]
	s_mov_b64 s[12:13], exec
	v_mbcnt_lo_u32_b32 v0, s12, 0
	v_mbcnt_hi_u32_b32 v0, s13, v0
	v_cmp_eq_u32_e32 vcc, 0, v0
	s_waitcnt vmcnt(0)
	s_and_saveexec_b64 s[14:15], vcc
	s_cbranch_execz .LBB0_1755
	s_bcnt1_i32_b64 s3, s[12:13]
	v_mov_b32_e32 v0, 0x2000
	v_mov_b32_e32 v1, s3
	global_atomic_add v0, v1, s[10:11] offset:1024

.LBB0_1775:
	s_andn2_b64 vcc, exec, s[12:13]
	s_cbranch_vccnz .LBB0_1827
	v_ashrrev_i32_e32 v0, 31, v8
	v_lshrrev_b32_e32 v0, 26, v0
	v_add_u32_e32 v0, v8, v0
	s_waitcnt lgkmcnt(0)
	v_ashrrev_i32_e32 v1, 6, v0
	v_bfe_i32 v0, v8, 27, 1
	v_lshlrev_b32_e32 v2, 4, v8
	v_lshrrev_b32_e32 v0, 22, v0
	v_add_u32_e32 v0, v2, v0
	v_and_b32_e32 v0, 0xfffffc00, v0
	v_sub_u32_e32 v0, v2, v0
	v_lshrrev_b32_e32 v3, 4, v0
	v_readlane_b32 s10, v236, 6
	v_bitop3_b32 v3, v3, v0, 32 bitop3:0x6c
	s_add_u32 s3, s72, 0x1f00000
	v_readlane_b32 s11, v236, 7
	v_ashrrev_i32_e32 v4, 31, v3
	s_addc_u32 s4, s73, 0
	s_and_b64 s[24:25], s[10:11], s[0:1]
	v_readlane_b32 s0, v236, 8
	v_lshrrev_b32_e32 v4, 26, v4
	s_lshl_b32 s0, s0, 6
	v_add_u32_e32 v4, v3, v4
	s_add_u32 s0, s72, s0
	v_ashrrev_i32_e32 v5, 6, v4
	v_and_b32_e32 v4, 0xc0, v4
	s_addc_u32 s1, s73, 0
	v_sub_u32_e32 v3, v3, v4
	v_mov_b32_e32 v4, 1
	s_add_u32 s5, s0, 0x9a000
	v_lshlrev_b32_e32 v0, 3, v1
	v_lshlrev_b32_e32 v1, 5, v1
	v_ashrrev_i16_sdwa v3, v4, sext(v3) dst_sel:DWORD dst_unused:UNUSED_PAD src0_sel:DWORD src1_sel:BYTE_0
	s_addc_u32 s7, s1, 0
	v_and_b32_e32 v0, -16, v0
	v_and_b32_e32 v1, 32, v1
	v_bfe_i32 v3, v3, 0, 16
	v_add_u32_e32 v2, 0x2000, v2
	s_and_b64 s[0:1], s[24:25], exec
	v_add_u32_e32 v0, v5, v0
	v_add_lshl_u32 v1, v1, v3, 1
	v_ashrrev_i32_e32 v3, 31, v2
	v_lshlrev_b32_e32 v6, 1, v0
	v_lshrrev_b32_e32 v7, 2, v0
	v_and_b32_e32 v5, 3, v5
	s_mov_b32 s0, 0x1fffe0
	v_lshrrev_b32_e32 v3, 22, v3
	v_and_b32_e32 v6, 24, v6
	v_and_b32_e32 v7, 4, v7
	v_and_or_b32 v5, v0, s0, v5
	v_add_u32_e32 v3, v2, v3
	v_or3_b32 v5, v5, v7, v6
	v_ashrrev_i32_e32 v3, 10, v3
	v_lshl_add_u32 v128, v5, 11, v1
	v_mul_i32_i24_e32 v5, 0x400, v3
	v_sub_u32_e32 v2, v2, v5
	v_lshrrev_b32_e32 v5, 4, v2
	v_bitop3_b32 v5, v5, v2, 32 bitop3:0x6c
	v_ashrrev_i32_e32 v6, 31, v5
	v_lshrrev_b32_e32 v6, 26, v6
	v_lshlrev_b32_e32 v2, 3, v3
	v_add_u32_e32 v6, v5, v6
	v_and_b32_e32 v2, -16, v2
	v_ashrrev_i32_e32 v7, 6, v6
	s_cselect_b32 s27, s7, 0
	s_cselect_b32 s26, s5, 0
	v_add_u32_e32 v2, v7, v2
	v_and_b32_e32 v7, 3, v7
	s_ashr_i32 s15, s14, 6
	s_ashr_i32 s7, s6, 31
	v_and_b32_e32 v6, 0xc0, v6
	v_and_or_b32 v7, v2, s0, v7
	s_lshl_b32 s5, s15, 10
	s_lshl_b64 s[0:1], s[6:7], 19
	v_sub_u32_e32 v5, v5, v6
	s_add_u32 s0, s3, s0
	v_lshlrev_b32_e32 v3, 5, v3
	v_ashrrev_i16_sdwa v4, v4, sext(v5) dst_sel:DWORD dst_unused:UNUSED_PAD src0_sel:DWORD src1_sel:BYTE_0
	v_lshlrev_b32_e32 v5, 1, v2
	v_lshrrev_b32_e32 v6, 2, v2
	s_addc_u32 s1, s4, s1
	s_add_i32 s33, s5, 0
	v_and_b32_e32 v3, 32, v3
	v_bfe_i32 v4, v4, 0, 16
	v_and_b32_e32 v5, 24, v5
	v_and_b32_e32 v6, 4, v6
	s_add_i32 m0, s33, 0x10000
	v_or3_b32 v5, v7, v6, v5
	v_add_lshl_u32 v3, v3, v4, 1
	global_load_lds_dwordx4 v128, s[0:1]
	s_add_i32 m0, s33, 0x12000
	v_lshl_add_u32 v130, v5, 11, v3
	s_add_u32 s10, s0, 0x40000
	global_load_lds_dwordx4 v130, s[0:1]
	s_addc_u32 s11, s1, 0
	s_add_i32 m0, s33, 0x14000
	v_mov_b32_e32 v133, 0
	global_load_lds_dwordx4 v128, s[10:11]
	s_add_i32 m0, s33, 0x16000
	s_cmp_eq_u32 s6, s84
	global_load_lds_dwordx4 v130, s[10:11]
	s_cselect_b64 s[10:11], -1, 0
	s_and_b64 s[10:11], s[24:25], s[10:11]
	v_mov_b32_e32 v129, v133
	s_andn2_b64 vcc, exec, s[10:11]
	v_mov_b32_e32 v131, v133
	s_cbranch_vccnz .LBB0_1791
	s_and_saveexec_b64 s[10:11], s[22:23]
	s_cbranch_execz .LBB0_1790
	s_mov_b32 s7, 0x400001
	buffer_inv sc1
	v_mov_b32_e32 v4, 0
	s_branch .LBB0_1780

.LBB0_1788:
	s_ashr_i32 s3, s3, 3
	s_add_i32 s3, s5, s3
	s_ashr_i32 s4, s3, 31
	s_lshr_b32 s4, s4, 25
	s_add_i32 s4, s3, s4
	s_ashr_i32 s5, s4, 7
	s_and_b32 s4, s4, 0xffffff80
	s_sub_i32 s3, s3, s4
	s_bfe_i32 s4, s3, 0x80000
	s_bfe_u32 s4, s4, 0x3000c
	s_add_i32 s4, s3, s4
	s_bfe_i32 s6, s4, 0x80000
	s_and_b32 s4, s4, 0xf8
	s_sub_i32 s3, s3, s4
	s_lshl_b32 s5, s5, 3
	s_sext_i32_i8 s3, s3
	s_sext_i32_i16 s6, s6
	s_add_i32 s8, s5, s3
	v_readlane_b32 s4, v236, 4
	s_ashr_i32 s6, s6, 3
	s_mov_b64 s[12:13], -1
	v_readlane_b32 s5, v236, 5
	s_andn2_b64 vcc, exec, s[10:11]
	s_cbranch_vccz .LBB0_1771
	s_branch .LBB0_1775
.LBB0_1789:
	s_waitcnt lgkmcnt(0)
	s_waitcnt vmcnt(0)
.LBB0_1790:
	s_or_b64 exec, exec, s[10:11]
	s_barrier

.LBB0_1847:
	s_or_b64 exec, exec, s[12:13]
	v_cvt_f32_u32_e32 v4, v2
	s_waitcnt vmcnt(0)
	v_readfirstlane_b32 s3, v3
	v_sub_u32_e32 v3, 0, v2
	v_rcp_iflag_f32_e32 v4, v4
	v_add_u32_e32 v5, s3, v1
	v_mul_f32_e32 v4, 0x4f7ffffe, v4
	v_cvt_u32_f32_e32 v4, v4
	v_mul_lo_u32 v1, v3, v4
	v_mul_hi_u32 v1, v4, v1
	v_add_u32_e32 v1, v4, v1
	v_mul_hi_u32 v1, v5, v1
	v_mul_lo_u32 v3, v1, v2
	v_sub_u32_e32 v3, v5, v3
	v_add_u32_e32 v4, 1, v1
	v_cmp_ge_u32_e32 vcc, v3, v2
	s_nop 1
	v_cndmask_b32_e32 v1, v1, v4, vcc
	v_sub_u32_e32 v4, v3, v2
	v_cndmask_b32_e32 v3, v3, v4, vcc
	v_add_u32_e32 v4, 1, v1
	v_cmp_ge_u32_e32 vcc, v3, v2
	v_add_u32_e32 v3, 1, v5
	s_nop 0
	v_cndmask_b32_e32 v1, v1, v4, vcc
	v_mul_lo_u32 v4, v2, v1
	v_add_u32_e32 v2, v4, v2
	v_cmp_ne_u32_e32 vcc, v3, v2
	s_and_saveexec_b64 s[4:5], vcc
	s_xor_b64 s[10:11], exec, s[4:5]
	s_cbranch_execz .LBB0_1861
	s_waitcnt lgkmcnt(0)
	buffer_inv sc1
	v_mov_b32_e32 v0, 0x2000
	global_load_dword v0, v0, s[8:9] offset:1024 sc1
	s_add_u32 s16, s8, 0x2400
	s_addc_u32 s17, s9, 0
	s_waitcnt vmcnt(0)
	v_cmp_eq_u32_e32 vcc, v0, v1
	s_and_saveexec_b64 s[12:13], vcc
	s_cbranch_execz .LBB0_1860
	s_add_u32 s14, s72, 0x4200
	s_addc_u32 s15, s73, 0
	s_mov_b32 s3, 1
	s_mov_b64 s[20:21], 0
	v_mov_b32_e32 v0, 0
	s_branch .LBB0_1851

.LBB0_1963:
	s_or_b64 exec, exec, s[20:21]
	v_cvt_f32_u32_e32 v4, v2
	s_waitcnt vmcnt(0)
	v_readfirstlane_b32 s3, v3
	v_sub_u32_e32 v3, 0, v2
	v_rcp_iflag_f32_e32 v4, v4
	v_add_u32_e32 v5, s3, v1
	v_mul_f32_e32 v4, 0x4f7ffffe, v4
	v_cvt_u32_f32_e32 v4, v4
	v_mul_lo_u32 v1, v3, v4
	v_mul_hi_u32 v1, v4, v1
	v_add_u32_e32 v1, v4, v1
	v_mul_hi_u32 v1, v5, v1
	v_mul_lo_u32 v3, v1, v2
	v_sub_u32_e32 v3, v5, v3
	v_add_u32_e32 v4, 1, v1
	v_cmp_ge_u32_e32 vcc, v3, v2
	s_nop 1
	v_cndmask_b32_e32 v1, v1, v4, vcc
	v_sub_u32_e32 v4, v3, v2
	v_cndmask_b32_e32 v3, v3, v4, vcc
	v_add_u32_e32 v4, 1, v1
	v_cmp_ge_u32_e32 vcc, v3, v2
	v_add_u32_e32 v3, 1, v5
	s_nop 0
	v_cndmask_b32_e32 v1, v1, v4, vcc
	v_mul_lo_u32 v4, v2, v1
	v_add_u32_e32 v2, v4, v2
	v_cmp_ne_u32_e32 vcc, v3, v2
	s_and_saveexec_b64 s[16:17], vcc
	s_xor_b64 s[16:17], exec, s[16:17]
	s_cbranch_execz .LBB0_1977
	s_waitcnt lgkmcnt(0)
	buffer_inv sc1
	v_mov_b32_e32 v0, 0x2000
	global_load_dword v0, v0, s[6:7] offset:1024 sc1
	s_add_u32 s26, s6, 0x2400
	s_addc_u32 s27, s7, 0
	s_waitcnt vmcnt(0)
	v_cmp_eq_u32_e32 vcc, v0, v1
	s_and_saveexec_b64 s[20:21], vcc
	s_cbranch_execz .LBB0_1976
	s_add_u32 s24, s72, 0x4200
	s_addc_u32 s25, s73, 0
	s_mov_b32 s3, 1
	s_mov_b64 s[28:29], 0
	v_mov_b32_e32 v0, 0
	s_branch .LBB0_1967

.LBB0_1976:
	s_or_b64 exec, exec, s[20:21]
	s_waitcnt vmcnt(0)
	s_waitcnt vmcnt(0)
.LBB0_1977:
	s_andn2_saveexec_b64 s[16:17], s[16:17]
	s_cbranch_execz .LBB0_1997
	s_mov_b64 s[16:17], exec
	buffer_wbl2 sc1
	s_waitcnt lgkmcnt(0)
	s_waitcnt vmcnt(0)
	buffer_inv sc1
	v_mbcnt_lo_u32_b32 v1, s16, 0
	v_mbcnt_hi_u32_b32 v1, s17, v1
	v_cmp_eq_u32_e32 vcc, 0, v1
	s_and_saveexec_b64 s[20:21], vcc
	s_cbranch_execz .LBB0_1980
	s_bcnt1_i32_b64 s3, s[16:17]
	v_mov_b32_e32 v2, 0x7000
	v_mov_b32_e32 v3, s3
	global_atomic_add v2, v2, v3, s[72:73] offset:1024 sc0

.LBB0_1994:
	s_or_b64 exec, exec, s[16:17]
	s_mov_b64 s[16:17], exec
	v_mbcnt_lo_u32_b32 v0, s16, 0
	v_mbcnt_hi_u32_b32 v0, s17, v0
	v_cmp_eq_u32_e32 vcc, 0, v0
	s_waitcnt vmcnt(0)
	s_and_saveexec_b64 s[20:21], vcc
	s_cbranch_execz .LBB0_1996
	s_bcnt1_i32_b64 s3, s[16:17]
	v_mov_b32_e32 v0, 0x2000
	v_mov_b32_e32 v1, s3
	global_atomic_add v0, v1, s[6:7] offset:1024

.LBB0_2003:
	s_and_b64 vcc, exec, s[4:5]
	s_cbranch_vccz .LBB0_2015
	s_cmp_gt_i32 s84, 3
	v_readfirstlane_b32 s38, v182
	s_cbranch_scc1 .LBB0_2015
	v_ashrrev_i32_e32 v0, 31, v182
	v_lshrrev_b32_e32 v0, 26, v0
	v_add_u32_e32 v0, v182, v0
	v_ashrrev_i32_e32 v1, 6, v0
	v_bfe_i32 v0, v182, 27, 1
	v_lshlrev_b32_e32 v2, 4, v182
	v_lshrrev_b32_e32 v0, 22, v0
	v_add_u32_e32 v0, v2, v0
	v_and_b32_e32 v0, 0xfffffc00, v0
	v_sub_u32_e32 v0, v2, v0
	v_lshrrev_b32_e32 v3, 4, v0
	v_bitop3_b32 v3, v3, v0, 32 bitop3:0x6c
	v_ashrrev_i32_e32 v4, 31, v3
	v_lshrrev_b32_e32 v4, 26, v4
	v_add_u32_e32 v4, v3, v4
	v_ashrrev_i32_e32 v5, 6, v4
	v_and_b32_e32 v4, 0xc0, v4
	v_sub_u32_e32 v3, v3, v4
	v_mov_b32_e32 v4, 1
	v_lshlrev_b32_e32 v0, 3, v1
	v_lshlrev_b32_e32 v1, 5, v1
	v_ashrrev_i16_sdwa v3, v4, sext(v3) dst_sel:DWORD dst_unused:UNUSED_PAD src0_sel:DWORD src1_sel:BYTE_0
	v_and_b32_e32 v1, 32, v1
	v_bfe_i32 v3, v3, 0, 16
	v_add_u32_e32 v2, 0x2000, v2
	v_add_lshl_u32 v1, v1, v3, 1
	v_ashrrev_i32_e32 v3, 31, v2
	v_lshrrev_b32_e32 v3, 22, v3
	v_add_u32_e32 v3, v2, v3
	v_ashrrev_i32_e32 v3, 10, v3
	v_mul_i32_i24_e32 v6, 0x400, v3
	v_sub_u32_e32 v2, v2, v6
	v_lshrrev_b32_e32 v6, 4, v2
	v_bitop3_b32 v6, v6, v2, 32 bitop3:0x6c
	v_ashrrev_i32_e32 v7, 31, v6
	v_lshrrev_b32_e32 v7, 26, v7
	v_add_u32_e32 v7, v6, v7
	v_ashrrev_i32_e32 v8, 6, v7
	v_and_b32_e32 v7, 0xc0, v7
	v_lshlrev_b32_e32 v2, 3, v3
	v_sub_u32_e32 v6, v6, v7
	v_and_b32_e32 v2, -16, v2
	v_lshlrev_b32_e32 v3, 5, v3
	v_ashrrev_i16_sdwa v4, v4, sext(v6) dst_sel:DWORD dst_unused:UNUSED_PAD src0_sel:DWORD src1_sel:BYTE_0
	v_add_u32_e32 v2, v8, v2
	v_and_b32_e32 v3, 32, v3
	v_bfe_i32 v4, v4, 0, 16
	v_add_lshl_u32 v3, v3, v4, 1
	v_and_b32_e32 v4, 3, v8
	s_mov_b32 s2, 0x7ffe0
	v_lshrrev_b32_e32 v6, 2, v2
	v_lshlrev_b32_e32 v7, 1, v2
	v_and_or_b32 v4, v2, s2, v4
	v_and_b32_e32 v6, 4, v6
	v_and_b32_e32 v7, 24, v7
	v_and_b32_e32 v0, -16, v0
	v_or3_b32 v4, v4, v6, v7
	s_ashr_i32 s33, s38, 6
	v_add_u32_e32 v0, v5, v0
	v_lshl_add_u32 v128, v4, 13, v3
	v_and_b32_e32 v4, 3, v5
	s_ashr_i32 s85, s84, 31
	s_lshl_b32 s39, s33, 10
	v_and_or_b32 v4, v0, s2, v4
	v_lshrrev_b32_e32 v5, 2, v0
	v_lshlrev_b32_e32 v6, 1, v0
	s_lshl_b64 s[2:3], s[84:85], 21
	v_and_b32_e32 v5, 4, v5
	v_and_b32_e32 v6, 24, v6
	s_add_u32 s4, s61, s2
	v_or3_b32 v4, v4, v5, v6
	s_addc_u32 s5, s62, s3
	s_add_i32 s40, s39, 0
	v_lshl_add_u32 v130, v4, 13, v1
	s_add_i32 m0, s40, 0x10000
	v_mov_b32_e32 v133, 0
	global_load_lds_dwordx4 v130, s[4:5]
	s_add_i32 m0, s40, 0x12000
	s_add_u32 s2, s4, 0x100000
	global_load_lds_dwordx4 v128, s[4:5]
	s_addc_u32 s3, s5, 0
	s_add_i32 m0, s40, 0x14000
	v_mov_b32_e32 v131, v133
	global_load_lds_dwordx4 v130, s[2:3]
	s_add_i32 m0, s40, 0x16000
	s_andn2_b64 vcc, exec, s[18:19]
	global_load_lds_dwordx4 v128, s[2:3]
	v_mov_b32_e32 v129, v133
	s_cbranch_vccnz .LBB0_2018
	s_and_saveexec_b64 s[2:3], s[22:23]
	s_cbranch_execz .LBB0_2017
	s_mov_b32 s16, 0x400001
	buffer_inv sc1
	v_mov_b32_e32 v4, 0
	s_branch .LBB0_2009

.LBB0_2015:
	s_endpgm
.LBB0_2016:
	s_waitcnt lgkmcnt(0)
	s_waitcnt vmcnt(0)
.LBB0_2017:
	s_or_b64 exec, exec, s[2:3]
	s_barrier
